# XCD-local barrier as a single arrival counter per XCC (fire-and-forget atomic, every workgroup polls the count; no leader / release hop)
# speedup vs baseline: 1.0047x; 1.0047x over previous
.Lxl_keep:
	s_nop 0
	v_writelane_b32 v255, s92, 10
	v_writelane_b32 v255, s101, 60
	s_mov_b32 s98, 0
	s_nop 0
	v_writelane_b32 v255, s98, 61
	s_branch .LBB0_147

.LBB0_686:
	s_andn2_b64 vcc, exec, s[0:1]
	s_cbranch_vccnz .LBB0_145
	s_waitcnt vmcnt(0)
	s_waitcnt lgkmcnt(0)
	s_barrier
	s_mov_b64 s[0:1], exec
	v_readlane_b32 s2, v254, 4
	v_readlane_b32 s3, v254, 5
	s_and_b64 s[2:3], s[0:1], s[2:3]
	s_mov_b64 exec, s[2:3]
	s_cbranch_execz .LBB0_144
	v_readlane_b32 s4, v255, 60
	s_lshr_b32 s5, 0x7fd6, s75
	s_and_b32 s5, s5, 1
	s_nop 0
	s_cmp_eq_u32 s4, 0
	s_cselect_b32 s5, s5, 0
	s_cmp_eq_u32 s5, 1
	s_cbranch_scc0 .Lfb_std
	v_readlane_b32 s2, v254, 56
	v_readlane_b32 s3, v254, 57
	s_getreg_b32 s4, hwreg(HW_REG_XCC_ID, 0, 4)
	s_lshl_b32 s4, s4, 4
	s_addk_i32 s4, 0x130
	s_add_u32 s2, s2, s4
	s_addc_u32 s3, s3, 0
	v_readlane_b32 s5, v255, 61
	v_mov_b32_e32 v1, 1
	s_nop 1
	global_atomic_add v0, v1, s[2:3]
	buffer_inv sc1
	s_add_i32 s5, s5, 1
	s_nop 0
	v_writelane_b32 v255, s5, 61
	s_lshl_b32 s5, s5, 5
	s_mov_b32 s4, 0
.Lfb_spin:
	global_load_dword v1, v0, s[2:3] sc1
	s_waitcnt vmcnt(0)
	v_readfirstlane_b32 s6, v1
	s_nop 3
	s_cmp_ge_u32 s6, s5
	s_cbranch_scc1 .LBB0_144
	s_sleep 1
	s_add_i32 s4, s4, 1
	s_cmp_lt_u32 s4, 0x8000
	s_cbranch_scc1 .Lfb_spin
	s_branch .LBB0_144
.Lfb_std:
	v_readlane_b32 s2, v255, 8
	s_waitcnt vmcnt(0) expcnt(0) lgkmcnt(0)
	s_nop 0
	v_mov_b32_e32 v1, s2
	ds_read_b32 v3, v1
	v_readlane_b32 s2, v255, 9
	s_waitcnt lgkmcnt(0)
	v_cmp_ne_u32_e32 vcc, 0, v3
	v_mov_b32_e32 v1, s2
	ds_read_b32 v2, v1
	s_cbranch_vccnz .LBB0_703
	s_mov_b32 s27, 1
	s_branch .LBB0_691
